# L3 xBC conv tile load: 5 serialized load-wait-LDS-store round trips per lane replaced by all row loads in flight then LDS stores
# speedup vs baseline: 1.0666x; 1.0059x over previous
.LBB0_737:
	s_mul_hi_i32 s2, s30, 0x2aaaaaab
	s_lshr_b32 s16, s2, 31
	s_ashr_i32 s2, s2, 2
	s_add_i32 s16, s2, s16
	s_mul_i32 s2, s16, 24
	s_sub_i32 s2, s30, s2
	s_lshl_b32 s18, s2, 6
	s_lshl_b32 s17, s16, 7
	s_barrier
	s_and_saveexec_b64 s[20:21], s[6:7]
	s_cbranch_execz .LBB0_742
	s_and_b32 s19, s16, 1
	s_and_b32 s26, s16, 31
	s_cmp_eq_u32 s19, 0
	s_cselect_b64 s[22:23], -1, 0
	s_cmp_lg_u32 s26, 31
	s_cselect_b64 s[24:25], -1, 0
	s_cmpk_lt_i32 s30, 0x300
	v_cndmask_b32_e64 v0, 0, 1, s[24:25]
	v_cndmask_b32_e64 v1, 0, 1, s[22:23]
	s_cselect_b32 s19, s19, s26
	v_readfirstlane_b32 s22, v1
	v_readfirstlane_b32 s23, v0
	s_cselect_b32 s24, s22, s23
	s_cmp_lg_u32 s19, 0
	s_cselect_b64 s[22:23], -1, 0
	s_bitcmp1_b32 s24, 0
	s_cselect_b64 s[24:25], -1, 0
	s_add_i32 s39, s17, -1
	s_ashr_i32 s19, s18, 31
	s_mov_b64 s[26:27], 0
	v_mov_b32_e32 v4, v52
	v_mov_b32_e32 v5, v45
	v_mov_b32_e32 v248, v45
	v_ashrrev_i32_e32 v249, 3, v248
	v_mov_b32_e32 v254, v52
	v_and_b32_e32 v254, 56, v254
	v_mul_lo_u32 v200, v249, s53
	v_lshl_add_u32 v200, v254, 1, v200
	v_mov_b32_e32 v228, 0
	v_mov_b32_e32 v229, 0
	v_mov_b32_e32 v230, 0
	v_mov_b32_e32 v231, 0
	v_cmp_lt_u32_e32 vcc, 7, v248
	s_nop 0
	s_or_b64 s[28:29], s[22:23], vcc
	v_cmp_ne_u32_e32 vcc, 0x81, v249
	s_nop 0
	s_or_b64 s[40:41], s[24:25], vcc
	s_and_b64 s[40:41], s[28:29], s[40:41]
	s_and_saveexec_b64 s[28:29], s[40:41]
	s_cbranch_execz .Ll3ld_skip0
	v_add_u32_e32 v253, s39, v249
	v_mov_b64_e32 v[228:229], s[4:5]
	v_mad_i64_i32 v[228:229], s[40:41], v253, s33, v[228:229]
	v_lshl_add_u64 v[228:229], s[18:19], 1, v[228:229]
	v_lshlrev_b32_e32 v254, 1, v254
	v_mov_b32_e32 v255, 0
	v_lshl_add_u64 v[228:229], v[228:229], 0, v[254:255]
	v_add_co_u32_e32 v228, vcc, 0x1000, v228
	s_nop 1
	v_addc_co_u32_e32 v229, vcc, 0, v229, vcc
	global_load_dwordx4 v[228:231], v[228:229], off offset:1024
.Ll3ld_skip0:
	s_or_b64 exec, exec, s[28:29]
	v_add_u32_e32 v248, 0x100, v45
	v_ashrrev_i32_e32 v249, 3, v248
	v_add_u32_e32 v254, 0x800, v52
	v_and_b32_e32 v254, 56, v254
	v_mul_lo_u32 v201, v249, s53
	v_lshl_add_u32 v201, v254, 1, v201
	v_mov_b32_e32 v232, 0
	v_mov_b32_e32 v233, 0
	v_mov_b32_e32 v234, 0
	v_mov_b32_e32 v235, 0
	v_cmp_lt_u32_e32 vcc, 7, v248
	s_nop 0
	s_or_b64 s[28:29], s[22:23], vcc
	v_cmp_ne_u32_e32 vcc, 0x81, v249
	s_nop 0
	s_or_b64 s[40:41], s[24:25], vcc
	s_and_b64 s[40:41], s[28:29], s[40:41]
	s_and_saveexec_b64 s[28:29], s[40:41]
	s_cbranch_execz .Ll3ld_skip1
	v_add_u32_e32 v253, s39, v249
	v_mov_b64_e32 v[232:233], s[4:5]
	v_mad_i64_i32 v[232:233], s[40:41], v253, s33, v[232:233]
	v_lshl_add_u64 v[232:233], s[18:19], 1, v[232:233]
	v_lshlrev_b32_e32 v254, 1, v254
	v_mov_b32_e32 v255, 0
	v_lshl_add_u64 v[232:233], v[232:233], 0, v[254:255]
	v_add_co_u32_e32 v232, vcc, 0x1000, v232
	s_nop 1
	v_addc_co_u32_e32 v233, vcc, 0, v233, vcc
	global_load_dwordx4 v[232:235], v[232:233], off offset:1024
.Ll3ld_skip1:
	s_or_b64 exec, exec, s[28:29]
	v_add_u32_e32 v248, 0x200, v45
	v_ashrrev_i32_e32 v249, 3, v248
	v_add_u32_e32 v254, 0x1000, v52
	v_and_b32_e32 v254, 56, v254
	v_mul_lo_u32 v202, v249, s53
	v_lshl_add_u32 v202, v254, 1, v202
	v_mov_b32_e32 v236, 0
	v_mov_b32_e32 v237, 0
	v_mov_b32_e32 v238, 0
	v_mov_b32_e32 v239, 0
	v_cmp_lt_u32_e32 vcc, 7, v248
	s_nop 0
	s_or_b64 s[28:29], s[22:23], vcc
	v_cmp_ne_u32_e32 vcc, 0x81, v249
	s_nop 0
	s_or_b64 s[40:41], s[24:25], vcc
	s_and_b64 s[40:41], s[28:29], s[40:41]
	s_and_saveexec_b64 s[28:29], s[40:41]
	s_cbranch_execz .Ll3ld_skip2
	v_add_u32_e32 v253, s39, v249
	v_mov_b64_e32 v[236:237], s[4:5]
	v_mad_i64_i32 v[236:237], s[40:41], v253, s33, v[236:237]
	v_lshl_add_u64 v[236:237], s[18:19], 1, v[236:237]
	v_lshlrev_b32_e32 v254, 1, v254
	v_mov_b32_e32 v255, 0
	v_lshl_add_u64 v[236:237], v[236:237], 0, v[254:255]
	v_add_co_u32_e32 v236, vcc, 0x1000, v236
	s_nop 1
	v_addc_co_u32_e32 v237, vcc, 0, v237, vcc
	global_load_dwordx4 v[236:239], v[236:237], off offset:1024
.Ll3ld_skip2:
	s_or_b64 exec, exec, s[28:29]
	v_add_u32_e32 v248, 0x300, v45
	v_ashrrev_i32_e32 v249, 3, v248
	v_add_u32_e32 v254, 0x1800, v52
	v_and_b32_e32 v254, 56, v254
	v_mul_lo_u32 v203, v249, s53
	v_lshl_add_u32 v203, v254, 1, v203
	v_mov_b32_e32 v240, 0
	v_mov_b32_e32 v241, 0
	v_mov_b32_e32 v242, 0
	v_mov_b32_e32 v243, 0
	v_cmp_lt_u32_e32 vcc, 7, v248
	s_nop 0
	s_or_b64 s[28:29], s[22:23], vcc
	v_cmp_ne_u32_e32 vcc, 0x81, v249
	s_nop 0
	s_or_b64 s[40:41], s[24:25], vcc
	s_and_b64 s[40:41], s[28:29], s[40:41]
	s_and_saveexec_b64 s[28:29], s[40:41]
	s_cbranch_execz .Ll3ld_skip3
	v_add_u32_e32 v253, s39, v249
	v_mov_b64_e32 v[240:241], s[4:5]
	v_mad_i64_i32 v[240:241], s[40:41], v253, s33, v[240:241]
	v_lshl_add_u64 v[240:241], s[18:19], 1, v[240:241]
	v_lshlrev_b32_e32 v254, 1, v254
	v_mov_b32_e32 v255, 0
	v_lshl_add_u64 v[240:241], v[240:241], 0, v[254:255]
	v_add_co_u32_e32 v240, vcc, 0x1000, v240
	s_nop 1
	v_addc_co_u32_e32 v241, vcc, 0, v241, vcc
	global_load_dwordx4 v[240:243], v[240:241], off offset:1024
.Ll3ld_skip3:
	s_or_b64 exec, exec, s[28:29]
	v_add_u32_e32 v248, 0x400, v45
	v_ashrrev_i32_e32 v249, 3, v248
	v_add_u32_e32 v254, 0x2000, v52
	v_and_b32_e32 v254, 56, v254
	v_mul_lo_u32 v227, v249, s53
	v_lshl_add_u32 v227, v254, 1, v227
	v_mov_b32_e32 v244, 0
	v_mov_b32_e32 v245, 0
	v_mov_b32_e32 v246, 0
	v_mov_b32_e32 v247, 0
	v_cmp_lt_u32_e32 vcc, 7, v248
	s_nop 0
	s_or_b64 s[28:29], s[22:23], vcc
	v_cmp_ne_u32_e32 vcc, 0x81, v249
	s_nop 0
	s_or_b64 s[40:41], s[24:25], vcc
	s_and_b64 s[40:41], s[28:29], s[40:41]
	v_cmp_gt_u32_e32 vcc, 0x410, v248
	s_nop 0
	s_and_b64 s[40:41], s[40:41], vcc
	s_and_saveexec_b64 s[28:29], s[40:41]
	s_cbranch_execz .Ll3ld_skip4
	v_add_u32_e32 v253, s39, v249
	v_mov_b64_e32 v[244:245], s[4:5]
	v_mad_i64_i32 v[244:245], s[40:41], v253, s33, v[244:245]
	v_lshl_add_u64 v[244:245], s[18:19], 1, v[244:245]
	v_lshlrev_b32_e32 v254, 1, v254
	v_mov_b32_e32 v255, 0
	v_lshl_add_u64 v[244:245], v[244:245], 0, v[254:255]
	v_add_co_u32_e32 v244, vcc, 0x1000, v244
	s_nop 1
	v_addc_co_u32_e32 v245, vcc, 0, v245, vcc
	global_load_dwordx4 v[244:247], v[244:245], off offset:1024
.Ll3ld_skip4:
	s_or_b64 exec, exec, s[28:29]
	s_waitcnt vmcnt(3)
	ds_write_b128 v200, v[228:231]
	s_waitcnt vmcnt(2)
	ds_write_b128 v201, v[232:235]
	s_waitcnt vmcnt(1)
	ds_write_b128 v202, v[236:239]
	s_waitcnt vmcnt(0)
	ds_write_b128 v203, v[240:243]
	v_add_u32_e32 v248, 0x400, v45
	v_cmp_gt_u32_e32 vcc, 0x410, v248
	s_and_saveexec_b64 s[28:29], vcc
	s_waitcnt vmcnt(0)
	ds_write_b128 v227, v[244:247]
	s_or_b64 exec, exec, s[28:29]

	.amdhsa_kernel _Z10fwd_kernel6Params
		.amdhsa_group_segment_fixed_size 73744
		.amdhsa_private_segment_fixed_size 0
		.amdhsa_kernarg_size 536
		.amdhsa_user_sgpr_count 2
		.amdhsa_user_sgpr_dispatch_ptr 0
		.amdhsa_user_sgpr_queue_ptr 0
		.amdhsa_user_sgpr_kernarg_segment_ptr 1
		.amdhsa_user_sgpr_dispatch_id 0
		.amdhsa_user_sgpr_kernarg_preload_length 0
		.amdhsa_user_sgpr_kernarg_preload_offset 0
		.amdhsa_user_sgpr_private_segment_size 0
		.amdhsa_uses_dynamic_stack 0
		.amdhsa_enable_private_segment 0
		.amdhsa_system_sgpr_workgroup_id_x 1
		.amdhsa_system_sgpr_workgroup_id_y 0
		.amdhsa_system_sgpr_workgroup_id_z 0
		.amdhsa_system_sgpr_workgroup_info 0
		.amdhsa_system_vgpr_workitem_id 2
		.amdhsa_next_free_vgpr 256
		.amdhsa_next_free_sgpr 102
		.amdhsa_accum_offset 256
		.amdhsa_reserve_vcc 1
		.amdhsa_float_round_mode_32 0
		.amdhsa_float_round_mode_16_64 0
		.amdhsa_float_denorm_mode_32 3
		.amdhsa_float_denorm_mode_16_64 3
		.amdhsa_dx10_clamp 1
		.amdhsa_ieee_mode 1
		.amdhsa_fp16_overflow 0
		.amdhsa_tg_split 0
		.amdhsa_exception_fp_ieee_invalid_op 0
		.amdhsa_exception_fp_denorm_src 0
		.amdhsa_exception_fp_ieee_div_zero 0
		.amdhsa_exception_fp_ieee_overflow 0
		.amdhsa_exception_fp_ieee_underflow 0
		.amdhsa_exception_fp_ieee_inexact 0
		.amdhsa_exception_int_div_zero 0
	.end_amdhsa_kernel

amdhsa.kernels:
  - .agpr_count:     0
    .args:
      - .offset:         0
        .size:           280
        .value_kind:     by_value
      - .offset:         280
        .size:           4
        .value_kind:     hidden_block_count_x
      - .offset:         284
        .size:           4
        .value_kind:     hidden_block_count_y
      - .offset:         288
        .size:           4
        .value_kind:     hidden_block_count_z
      - .offset:         292
        .size:           2
        .value_kind:     hidden_group_size_x
      - .offset:         294
        .size:           2
        .value_kind:     hidden_group_size_y
      - .offset:         296
        .size:           2
        .value_kind:     hidden_group_size_z
      - .offset:         298
        .size:           2
        .value_kind:     hidden_remainder_x
      - .offset:         300
        .size:           2
        .value_kind:     hidden_remainder_y
      - .offset:         302
        .size:           2
        .value_kind:     hidden_remainder_z
      - .offset:         320
        .size:           8
        .value_kind:     hidden_global_offset_x
      - .offset:         328
        .size:           8
        .value_kind:     hidden_global_offset_y
      - .offset:         336
        .size:           8
        .value_kind:     hidden_global_offset_z
      - .offset:         344
        .size:           2
        .value_kind:     hidden_grid_dims
      - .offset:         368
        .size:           8
        .value_kind:     hidden_multigrid_sync_arg
    .group_segment_fixed_size: 73744
    .kernarg_segment_align: 8
    .kernarg_segment_size: 536
    .language:       OpenCL C
    .language_version:
      - 2
      - 0
    .max_flat_workgroup_size: 256
    .name:           _Z10fwd_kernel6Params
    .private_segment_fixed_size: 0
    .sgpr_count:     108
    .sgpr_spill_count: 234
    .symbol:         _Z10fwd_kernel6Params.kd
    .uniform_work_group_size: 1
    .uses_dynamic_stack: false
    .vgpr_count:     256
    .vgpr_spill_count: 0
    .wavefront_size: 64
